# attention steady steps: first two PV MFMAs hoisted into the row-max section, 32 exps spread over the remaining fourteen
# baseline (speedup 1.0000x reference)
.LBB0_973:
	s_lshl_b32 s40, s2, 1
	v_add_u32_e32 v216, s40, v242
	ds_read_b64_tr_b16 v[210:211], v216 offset:24576
	ds_read_b64_tr_b16 v[212:213], v216 offset:25088
	s_waitcnt lgkmcnt(9)
	v_mfma_f32_32x32x16_bf16 v[130:145], v[206:209], v[174:177], v[66:81]
	v_add_f32_e32 v114, v98, v99
	v_add_f32_e32 v114, v100, v114
	v_add_f32_e32 v114, v101, v114
	v_add_f32_e32 v114, v102, v114
	v_add_f32_e32 v114, v103, v114
	v_cvt_pk_bf16_f32 v158, v98, v99
	v_cvt_pk_bf16_f32 v159, v100, v101
	ds_read_b64_tr_b16 v[206:207], v216 offset:28672
	ds_read_b64_tr_b16 v[208:209], v216 offset:29184
	v_add_f32_e32 v98, v104, v114
	s_waitcnt lgkmcnt(10)
	v_mfma_f32_32x32x16_bf16 v[114:129], v[202:205], v[174:177], v[66:81]
	v_add_f32_e32 v98, v105, v98
	v_add_f32_e32 v98, v106, v98
	v_add_f32_e32 v146, v107, v98
	v_cvt_pk_bf16_f32 v160, v102, v103
	v_cvt_pk_bf16_f32 v161, v104, v105
	ds_read_b64_tr_b16 v[98:99], v216 offset:25600
	ds_read_b64_tr_b16 v[100:101], v216 offset:26112
	s_waitcnt lgkmcnt(11)
	v_mfma_f32_32x32x16_bf16 v[130:145], v[198:201], v[170:173], v[130:145]
	v_add_f32_e32 v102, v108, v146
	v_add_f32_e32 v102, v109, v102
	v_add_f32_e32 v102, v110, v102
	v_add_f32_e32 v146, v111, v102
	v_cvt_pk_bf16_f32 v154, v106, v107
	v_cvt_pk_bf16_f32 v155, v108, v109
	ds_read_b64_tr_b16 v[102:103], v216 offset:29696
	ds_read_b64_tr_b16 v[104:105], v216 offset:30208
	s_waitcnt lgkmcnt(12)
	v_mfma_f32_32x32x16_bf16 v[114:129], v[194:197], v[170:173], v[114:129]
	v_add_f32_e32 v106, v112, v146
	v_add_f32_e32 v106, v113, v106
	v_add_f32_e32 v106, v82, v106
	v_add_f32_e32 v146, v83, v106
	v_cvt_pk_bf16_f32 v156, v110, v111
	v_cvt_pk_bf16_f32 v157, v112, v113
	ds_read_b64_tr_b16 v[106:107], v216 offset:26624
	ds_read_b64_tr_b16 v[108:109], v216 offset:27136
	s_waitcnt lgkmcnt(13)
	v_mfma_f32_32x32x16_bf16 v[130:145], v[190:193], v[166:169], v[130:145]
	v_add_f32_e32 v110, v84, v146
	v_add_f32_e32 v110, v85, v110
	v_add_f32_e32 v110, v86, v110
	v_add_f32_e32 v146, v87, v110
	v_cvt_pk_bf16_f32 v150, v82, v83
	v_cvt_pk_bf16_f32 v151, v84, v85
	ds_read_b64_tr_b16 v[110:111], v216 offset:30720
	ds_read_b64_tr_b16 v[112:113], v216 offset:31232
	s_waitcnt lgkmcnt(14)
	v_mfma_f32_32x32x16_bf16 v[114:129], v[186:189], v[166:169], v[114:129]
	v_add_f32_e32 v82, v88, v146
	v_add_f32_e32 v82, v89, v82
	v_add_f32_e32 v82, v90, v82
	v_add_f32_e32 v82, v91, v82
	v_cvt_pk_bf16_f32 v152, v86, v87
	v_cvt_pk_bf16_f32 v153, v88, v89
	ds_read_b64_tr_b16 v[86:87], v216 offset:27648
	ds_read_b64_tr_b16 v[88:89], v216 offset:28160
	s_waitcnt lgkmcnt(14)
	v_mfma_f32_32x32x16_bf16 v[130:145], v[182:185], v[162:165], v[130:145]
	v_add_f32_e32 v82, v92, v82
	v_add_f32_e32 v82, v93, v82
	v_add_f32_e32 v82, v94, v82
	v_add_f32_e32 v82, v95, v82
	v_cvt_pk_bf16_f32 v146, v90, v91
	v_cvt_pk_bf16_f32 v147, v92, v93
	ds_read_b64_tr_b16 v[90:91], v216 offset:31744
	ds_read_b64_tr_b16 v[92:93], v216 offset:32256
	v_mfma_f32_32x32x16_bf16 v[114:129], v[178:181], v[162:165], v[114:129]
	v_add_f32_e32 v82, v96, v82
	v_add_f32_e32 v82, v97, v82
	v_add_f32_e32 v84, 0, v82
	v_cvt_pk_bf16_f32 v148, v94, v95
	v_cvt_pk_bf16_f32 v149, v96, v97
	v_lshl_add_u64 v[218:219], v[226:227], 0, s[16:17]
	v_lshl_add_u64 v[82:83], v[218:219], 0, s[30:31]
	s_add_i32 s2, s46, s83
	v_lshl_add_u64 v[216:217], v[214:215], 0, s[16:17]
	s_mov_b32 s3, m0
	s_mov_b32 m0, s2
	s_nop 0
	global_load_lds_dwordx4 v[82:83], off
	s_mov_b32 m0, s3
	v_lshl_add_u64 v[82:83], v[216:217], 0, s[34:35]
	s_lshl_b32 s2, s44, 1
	s_add_i32 s2, s2, s84
	s_mov_b32 s3, m0
	s_mov_b32 m0, s2
	s_nop 0
	global_load_lds_dwordx4 v[82:83], off
	s_mov_b32 m0, s3
	v_lshl_add_u64 v[82:83], v[216:217], 0, s[36:37]
	s_addk_i32 s2, 0x2000
	s_mov_b32 s3, m0
	s_mov_b32 m0, s2
	s_nop 0
	global_load_lds_dwordx4 v[82:83], off
	s_mov_b32 m0, s3
	s_waitcnt lgkmcnt(14)
	v_mfma_f32_32x32x16_bf16 v[50:65], v[158:161], v[210:213], v[50:65]
	v_max_f32_e32 v82, v131, v131
	v_max_f32_e32 v83, v130, v130
	v_max_f32_e32 v82, v83, v82
	v_max3_f32 v83, v132, v133, v115
	v_max3_f32 v82, v82, v114, v116
	v_max3_f32 v82, v82, v117, v134
	v_max3_f32 v83, v83, v136, v137
	v_max3_f32 v82, v82, v135, v118
	v_max3_f32 v83, v83, v120, v121
	v_max3_f32 v82, v82, v119, v138
	s_waitcnt lgkmcnt(12)
	v_mfma_f32_32x32x16_bf16 v[34:49], v[158:161], v[206:209], v[34:49]
	v_max3_f32 v83, v83, v140, v141
	v_max3_f32 v82, v82, v139, v122
	v_max3_f32 v83, v83, v124, v125
	v_max3_f32 v82, v82, v123, v142
	v_max3_f32 v83, v83, v144, v145
	v_max3_f32 v82, v82, v143, v126
	v_max3_f32 v83, v83, v128, v129
	v_max3_f32 v82, v82, v127, v83
	v_mov_b32_e32 v83, v82
	s_nop 1
	v_permlane32_swap_b32_e32 v82, v83
	v_max_f32_e32 v83, v83, v83
	v_max_f32_e32 v82, v82, v82
	v_max_f32_e32 v82, v82, v83
	v_cmp_lt_f32_e32 vcc, s87, v82
	s_cmp_lg_u64 vcc, 0
	v_add_f32_e32 v230, v244, v84
	s_cselect_b64 s[2:3], -1, 0
	s_cbranch_vccnz .LBB0_981
.LBB0_974:
	v_add_u32_e32 v94, s44, v241
	ds_read_b128 v[82:85], v94
	ds_read_b128 v[198:201], v94 offset:512
	s_waitcnt lgkmcnt(12)
	v_mfma_f32_32x32x16_bf16 v[50:65], v[154:157], v[98:101], v[50:65]
	v_exp_f32_e32 v130, v130
	v_exp_f32_e32 v131, v131
	v_exp_f32_e32 v132, v132
	ds_read_b128 v[202:205], v94 offset:2048
	ds_read_b128 v[194:197], v94 offset:2560
	s_waitcnt lgkmcnt(12)
	v_mfma_f32_32x32x16_bf16 v[34:49], v[154:157], v[102:105], v[34:49]
	v_exp_f32_e32 v133, v133
	v_exp_f32_e32 v134, v134
	v_exp_f32_e32 v135, v135
	ds_read_b128 v[190:193], v94 offset:4096
	ds_read_b128 v[186:189], v94 offset:4608
	s_waitcnt lgkmcnt(12)
	v_mfma_f32_32x32x16_bf16 v[50:65], v[150:153], v[106:109], v[50:65]
	v_exp_f32_e32 v136, v136
	v_exp_f32_e32 v137, v137
	v_exp_f32_e32 v138, v138
	ds_read_b128 v[182:185], v94 offset:6144
	ds_read_b128 v[178:181], v94 offset:6656
	s_waitcnt lgkmcnt(12)
	v_mfma_f32_32x32x16_bf16 v[34:49], v[150:153], v[110:113], v[34:49]
	v_exp_f32_e32 v139, v139
	v_exp_f32_e32 v140, v140
	v_exp_f32_e32 v141, v141
	s_waitcnt lgkmcnt(10)
	v_mfma_f32_32x32x16_bf16 v[50:65], v[146:149], v[86:89], v[50:65]
	v_exp_f32_e32 v142, v142
	v_exp_f32_e32 v143, v143
	s_waitcnt lgkmcnt(8)
	v_mfma_f32_32x32x16_bf16 v[34:49], v[146:149], v[90:93], v[34:49]
	v_exp_f32_e32 v144, v144
	v_exp_f32_e32 v145, v145
	v_add_u32_e32 v102, s40, v228
	ds_read_b64_tr_b16 v[86:87],v102 offset:0
	ds_read_b64_tr_b16 v[88:89],v102 offset:512
	ds_read_b64_tr_b16 v[90:91],v102 offset:1024
	ds_read_b64_tr_b16 v[92:93],v102 offset:1536
	ds_read_b64_tr_b16 v[94:95],v102 offset:2048
	ds_read_b64_tr_b16 v[96:97],v102 offset:2560
	ds_read_b64_tr_b16 v[98:99],v102 offset:3072
	ds_read_b64_tr_b16 v[100:101],v102 offset:3584
	s_waitcnt lgkmcnt(0)
	s_nop 0
	v_mfma_f32_32x32x16_bf16 v[18:33], v[158:161], v[86:89], v[18:33]
	v_exp_f32_e32 v114, v114
	v_exp_f32_e32 v115, v115
	ds_read_b64_tr_b16 v[86:87],v102 offset:4096
	ds_read_b64_tr_b16 v[88:89],v102 offset:4608
	v_mfma_f32_32x32x16_bf16 v[18:33], v[154:157], v[90:93], v[18:33]
	v_exp_f32_e32 v116, v116
	v_exp_f32_e32 v117, v117
	ds_read_b64_tr_b16 v[90:91],v102 offset:5120
	ds_read_b64_tr_b16 v[92:93],v102 offset:5632
	v_mfma_f32_32x32x16_bf16 v[18:33], v[150:153], v[94:97], v[18:33]
	v_exp_f32_e32 v118, v118
	v_exp_f32_e32 v119, v119
	ds_read_b64_tr_b16 v[94:95],v102 offset:6144
	ds_read_b64_tr_b16 v[96:97],v102 offset:6656
	v_mfma_f32_32x32x16_bf16 v[18:33], v[146:149], v[98:101], v[18:33]
	v_exp_f32_e32 v120, v120
	v_exp_f32_e32 v121, v121
	ds_read_b64_tr_b16 v[98:99],v102 offset:7168
	ds_read_b64_tr_b16 v[100:101],v102 offset:7680
	s_waitcnt lgkmcnt(0)
	v_mfma_f32_32x32x16_bf16 v[2:17], v[158:161], v[86:89], v[2:17]
	v_exp_f32_e32 v122, v122
	v_exp_f32_e32 v123, v123
	s_waitcnt vmcnt(3) lgkmcnt(0)
	s_barrier
	s_andn2_b64 vcc, exec, s[2:3]
	v_add_u32_e32 v229, s94, v243
	v_mfma_f32_32x32x16_bf16 v[2:17], v[154:157], v[90:93], v[2:17]
	v_exp_f32_e32 v124, v124
	v_exp_f32_e32 v125, v125
	v_mfma_f32_32x32x16_bf16 v[2:17], v[150:153], v[94:97], v[2:17]
	v_exp_f32_e32 v126, v126
	v_exp_f32_e32 v127, v127
	v_mfma_f32_32x32x16_bf16 v[2:17], v[146:149], v[98:101], v[2:17]
	v_exp_f32_e32 v128, v128
	v_exp_f32_e32 v129, v129
	s_cbranch_vccnz .LBB0_976
	s_waitcnt lgkmcnt(0)
	ds_read_b128 v[86:89], v229 offset:96
	ds_read_b128 v[90:93], v229 offset:64
	ds_read_b128 v[94:97], v229 offset:32
	ds_read_b128 v[98:101], v229
	s_waitcnt lgkmcnt(3)
	v_pk_mul_f32 v[62:63], v[62:63], v[86:87]
	s_waitcnt lgkmcnt(2)
	v_pk_mul_f32 v[58:59], v[58:59], v[90:91]
	s_waitcnt lgkmcnt(1)
	v_pk_mul_f32 v[54:55], v[54:55], v[94:95]
	v_pk_mul_f32 v[64:65], v[64:65], v[88:89]
	v_pk_mul_f32 v[60:61], v[60:61], v[92:93]
	v_pk_mul_f32 v[56:57], v[56:57], v[96:97]
	s_waitcnt lgkmcnt(0)
	v_pk_mul_f32 v[52:53], v[52:53], v[100:101]
	v_pk_mul_f32 v[50:51], v[50:51], v[98:99]
	v_pk_mul_f32 v[46:47], v[46:47], v[86:87]
	v_pk_mul_f32 v[42:43], v[42:43], v[90:91]
	v_pk_mul_f32 v[38:39], v[38:39], v[94:95]
	v_pk_mul_f32 v[48:49], v[48:49], v[88:89]
	v_pk_mul_f32 v[44:45], v[44:45], v[92:93]
	v_pk_mul_f32 v[40:41], v[40:41], v[96:97]
	v_pk_mul_f32 v[36:37], v[36:37], v[100:101]
	v_pk_mul_f32 v[34:35], v[34:35], v[98:99]
	v_pk_mul_f32 v[30:31], v[30:31], v[86:87]
	v_pk_mul_f32 v[26:27], v[26:27], v[90:91]
	v_pk_mul_f32 v[22:23], v[22:23], v[94:95]
	v_pk_mul_f32 v[32:33], v[32:33], v[88:89]
	v_pk_mul_f32 v[28:29], v[28:29], v[92:93]
	v_pk_mul_f32 v[24:25], v[24:25], v[96:97]
	v_pk_mul_f32 v[20:21], v[20:21], v[100:101]
	v_pk_mul_f32 v[18:19], v[18:19], v[98:99]
	v_pk_mul_f32 v[14:15], v[14:15], v[86:87]
	v_pk_mul_f32 v[10:11], v[10:11], v[90:91]
	v_pk_mul_f32 v[6:7], v[6:7], v[94:95]
	v_pk_mul_f32 v[16:17], v[16:17], v[88:89]
	v_pk_mul_f32 v[12:13], v[12:13], v[92:93]
	v_pk_mul_f32 v[8:9], v[8:9], v[96:97]
	v_pk_mul_f32 v[4:5], v[4:5], v[100:101]
	v_pk_mul_f32 v[2:3], v[2:3], v[98:99]
.LBB0_976:
	s_add_i32 s2, s44, 0x2000
	s_cmpk_lg_i32 s44, 0x4000
	s_cselect_b32 s40, s2, 0
	s_lshl_b32 s45, s46, 1
	v_add_u32_e32 v231, s45, v242
	ds_read_b64_tr_b16 v[210:211], v231 offset:24576
	ds_read_b64_tr_b16 v[212:213], v231 offset:25088
	s_waitcnt lgkmcnt(9)
	v_mfma_f32_32x32x16_bf16 v[98:113], v[82:85], v[174:177], v[66:81]
	v_add_f32_e32 v86, v130, v131
	v_add_f32_e32 v86, v132, v86
	v_add_f32_e32 v86, v133, v86
	v_add_f32_e32 v86, v134, v86
	v_add_f32_e32 v86, v135, v86
	v_cvt_pk_bf16_f32 v158, v130, v131
	v_cvt_pk_bf16_f32 v159, v132, v133
	ds_read_b64_tr_b16 v[206:207], v231 offset:28672
	ds_read_b64_tr_b16 v[208:209], v231 offset:29184
	v_add_f32_e32 v82, v136, v86
	v_add_f32_e32 v82, v137, v82
	v_add_f32_e32 v82, v138, v82
	v_add_f32_e32 v146, v139, v82
	s_waitcnt lgkmcnt(10)
	v_mfma_f32_32x32x16_bf16 v[82:97], v[198:201], v[174:177], v[66:81]
	v_cvt_pk_bf16_f32 v160, v134, v135
	v_cvt_pk_bf16_f32 v161, v136, v137
	ds_read_b64_tr_b16 v[130:131], v231 offset:25600
	ds_read_b64_tr_b16 v[132:133], v231 offset:26112
	s_waitcnt lgkmcnt(11)
	v_mfma_f32_32x32x16_bf16 v[98:113], v[202:205], v[170:173], v[98:113]
	v_add_f32_e32 v134, v140, v146
	v_add_f32_e32 v134, v141, v134
	v_add_f32_e32 v134, v142, v134
	v_add_f32_e32 v146, v143, v134
	v_cvt_pk_bf16_f32 v154, v138, v139
	v_cvt_pk_bf16_f32 v155, v140, v141
	ds_read_b64_tr_b16 v[134:135], v231 offset:29696
	ds_read_b64_tr_b16 v[136:137], v231 offset:30208
	s_waitcnt lgkmcnt(12)
	v_mfma_f32_32x32x16_bf16 v[82:97], v[194:197], v[170:173], v[82:97]
	v_add_f32_e32 v138, v144, v146
	v_add_f32_e32 v138, v145, v138
	v_add_f32_e32 v138, v114, v138
	v_add_f32_e32 v146, v115, v138
	v_cvt_pk_bf16_f32 v156, v142, v143
	v_cvt_pk_bf16_f32 v157, v144, v145
	ds_read_b64_tr_b16 v[138:139], v231 offset:26624
	ds_read_b64_tr_b16 v[140:141], v231 offset:27136
	s_waitcnt lgkmcnt(13)
	v_mfma_f32_32x32x16_bf16 v[98:113], v[190:193], v[166:169], v[98:113]
	v_add_f32_e32 v142, v116, v146
	v_add_f32_e32 v142, v117, v142
	v_add_f32_e32 v142, v118, v142
	v_add_f32_e32 v142, v119, v142
	v_cvt_pk_bf16_f32 v150, v114, v115
	v_cvt_pk_bf16_f32 v151, v116, v117
	ds_read_b64_tr_b16 v[114:115], v231 offset:30720
	ds_read_b64_tr_b16 v[116:117], v231 offset:31232
	s_waitcnt lgkmcnt(14)
	v_mfma_f32_32x32x16_bf16 v[82:97], v[186:189], v[166:169], v[82:97]
	v_add_f32_e32 v142, v120, v142
	v_add_f32_e32 v142, v121, v142
	v_add_f32_e32 v142, v122, v142
	v_add_f32_e32 v142, v123, v142
	v_cvt_pk_bf16_f32 v152, v118, v119
	v_cvt_pk_bf16_f32 v153, v120, v121
	ds_read_b64_tr_b16 v[118:119], v231 offset:27648
	ds_read_b64_tr_b16 v[120:121], v231 offset:28160
	s_waitcnt lgkmcnt(14)
	v_mfma_f32_32x32x16_bf16 v[98:113], v[182:185], v[162:165], v[98:113]
	v_add_f32_e32 v142, v124, v142
	v_add_f32_e32 v142, v125, v142
	v_add_f32_e32 v142, v126, v142
	v_add_f32_e32 v142, v127, v142
	v_cvt_pk_bf16_f32 v146, v122, v123
	v_cvt_pk_bf16_f32 v147, v124, v125
	ds_read_b64_tr_b16 v[122:123], v231 offset:31744
	ds_read_b64_tr_b16 v[124:125], v231 offset:32256
	v_mfma_f32_32x32x16_bf16 v[82:97], v[178:181], v[162:165], v[82:97]
	v_add_f32_e32 v142, v128, v142
	v_add_f32_e32 v142, v129, v142
	v_add_f32_e32 v142, 0, v142
	v_cvt_pk_bf16_f32 v148, v126, v127
	v_cvt_pk_bf16_f32 v149, v128, v129
	s_mov_b64 s[2:3], 0x50000
	v_lshl_add_u64 v[126:127], v[218:219], 0, s[2:3]
	s_add_i32 s2, s44, s83
	s_mov_b32 s3, m0
	s_mov_b32 m0, s2
	s_nop 0
	global_load_lds_dwordx4 v[126:127], off
	s_mov_b32 m0, s3
	s_mov_b64 s[2:3], 0x5830000
	v_lshl_add_u64 v[126:127], v[216:217], 0, s[2:3]
	s_lshl_b32 s2, s40, 1
	s_add_i32 s46, s2, s84
	s_mov_b32 s2, m0
	s_mov_b32 m0, s46
	s_nop 0
	global_load_lds_dwordx4 v[126:127], off
	s_mov_b32 m0, s2
	s_mov_b64 s[2:3], 0x5830080
	v_lshl_add_u64 v[126:127], v[216:217], 0, s[2:3]
	s_add_i32 s2, s46, 0x2000
	s_mov_b32 s3, m0
	s_mov_b32 m0, s2
	s_nop 0
	global_load_lds_dwordx4 v[126:127], off
	s_mov_b32 m0, s3
	s_waitcnt lgkmcnt(14)
	v_mfma_f32_32x32x16_bf16 v[50:65], v[158:161], v[210:213], v[50:65]
	v_max_f32_e32 v126, v99, v99
	v_max_f32_e32 v127, v98, v98
	v_max_f32_e32 v126, v127, v126
	v_max3_f32 v127, v100, v101, v83
	v_max3_f32 v126, v126, v82, v84
	v_max3_f32 v126, v126, v85, v102
	v_max3_f32 v127, v127, v104, v105
	v_max3_f32 v126, v126, v103, v86
	v_max3_f32 v127, v127, v88, v89
	v_max3_f32 v126, v126, v87, v106
	s_waitcnt lgkmcnt(12)
	v_mfma_f32_32x32x16_bf16 v[34:49], v[158:161], v[206:209], v[34:49]
	v_max3_f32 v127, v127, v108, v109
	v_max3_f32 v126, v126, v107, v90
	v_max3_f32 v127, v127, v92, v93
	v_max3_f32 v126, v126, v91, v110
	v_max3_f32 v127, v127, v112, v113
	v_max3_f32 v126, v126, v111, v94
	v_max3_f32 v127, v127, v96, v97
	v_max3_f32 v126, v126, v95, v127
	v_mov_b32_e32 v127, v126
	s_nop 1
	v_permlane32_swap_b32_e32 v126, v127
	v_max_f32_e32 v127, v127, v127
	v_max_f32_e32 v126, v126, v126
	v_max_f32_e32 v126, v126, v127
	v_cmp_lt_f32_e32 vcc, s87, v126
	s_cmp_lg_u64 vcc, 0
	v_add_f32_e32 v244, v230, v142
	s_cselect_b64 s[2:3], -1, 0
	s_cbranch_vccnz .LBB0_984
.LBB0_977:
	v_add_u32_e32 v126, s40, v241
	ds_read_b128 v[206:209], v126
	ds_read_b128 v[202:205], v126 offset:512
	s_waitcnt lgkmcnt(12)
	v_mfma_f32_32x32x16_bf16 v[50:65], v[154:157], v[130:133], v[50:65]
	v_exp_f32_e32 v98, v98
	v_exp_f32_e32 v99, v99
	v_exp_f32_e32 v100, v100
	ds_read_b128 v[198:201], v126 offset:2048
	ds_read_b128 v[194:197], v126 offset:2560
	s_waitcnt lgkmcnt(12)
	v_mfma_f32_32x32x16_bf16 v[34:49], v[154:157], v[134:137], v[34:49]
	v_exp_f32_e32 v101, v101
	v_exp_f32_e32 v102, v102
	v_exp_f32_e32 v103, v103
	ds_read_b128 v[190:193], v126 offset:4096
	ds_read_b128 v[186:189], v126 offset:4608
	s_waitcnt lgkmcnt(12)
	v_mfma_f32_32x32x16_bf16 v[50:65], v[150:153], v[138:141], v[50:65]
	v_exp_f32_e32 v104, v104
	v_exp_f32_e32 v105, v105
	v_exp_f32_e32 v106, v106
	ds_read_b128 v[182:185], v126 offset:6144
	ds_read_b128 v[178:181], v126 offset:6656
	s_waitcnt lgkmcnt(12)
	v_mfma_f32_32x32x16_bf16 v[34:49], v[150:153], v[114:117], v[34:49]
	v_exp_f32_e32 v107, v107
	v_exp_f32_e32 v108, v108
	v_exp_f32_e32 v109, v109
	s_waitcnt lgkmcnt(10)
	v_mfma_f32_32x32x16_bf16 v[50:65], v[146:149], v[118:121], v[50:65]
	v_exp_f32_e32 v110, v110
	v_exp_f32_e32 v111, v111
	s_waitcnt lgkmcnt(8)
	v_mfma_f32_32x32x16_bf16 v[34:49], v[146:149], v[122:125], v[34:49]
	v_exp_f32_e32 v112, v112
	v_exp_f32_e32 v113, v113
	v_add_u32_e32 v130, s45, v228
	ds_read_b64_tr_b16 v[114:115],v130 offset:0
	ds_read_b64_tr_b16 v[116:117],v130 offset:512
	ds_read_b64_tr_b16 v[118:119],v130 offset:1024
	ds_read_b64_tr_b16 v[120:121],v130 offset:1536
	ds_read_b64_tr_b16 v[122:123],v130 offset:2048
	ds_read_b64_tr_b16 v[124:125],v130 offset:2560
	ds_read_b64_tr_b16 v[126:127],v130 offset:3072
	ds_read_b64_tr_b16 v[128:129],v130 offset:3584
	s_waitcnt lgkmcnt(0)
	s_nop 0
	v_mfma_f32_32x32x16_bf16 v[18:33], v[158:161], v[114:117], v[18:33]
	v_exp_f32_e32 v82, v82
	v_exp_f32_e32 v83, v83
	ds_read_b64_tr_b16 v[114:115],v130 offset:4096
	ds_read_b64_tr_b16 v[116:117],v130 offset:4608
	v_mfma_f32_32x32x16_bf16 v[18:33], v[154:157], v[118:121], v[18:33]
	v_exp_f32_e32 v84, v84
	v_exp_f32_e32 v85, v85
	ds_read_b64_tr_b16 v[118:119],v130 offset:5120
	ds_read_b64_tr_b16 v[120:121],v130 offset:5632
	v_mfma_f32_32x32x16_bf16 v[18:33], v[150:153], v[122:125], v[18:33]
	v_exp_f32_e32 v86, v86
	v_exp_f32_e32 v87, v87
	ds_read_b64_tr_b16 v[122:123],v130 offset:6144
	ds_read_b64_tr_b16 v[124:125],v130 offset:6656
	v_mfma_f32_32x32x16_bf16 v[18:33], v[146:149], v[126:129], v[18:33]
	v_exp_f32_e32 v88, v88
	v_exp_f32_e32 v89, v89
	ds_read_b64_tr_b16 v[126:127],v130 offset:7168
	ds_read_b64_tr_b16 v[128:129],v130 offset:7680
	s_waitcnt lgkmcnt(0)
	v_mfma_f32_32x32x16_bf16 v[2:17], v[158:161], v[114:117], v[2:17]
	v_exp_f32_e32 v90, v90
	v_exp_f32_e32 v91, v91
	s_waitcnt vmcnt(3) lgkmcnt(0)
	s_barrier
	s_andn2_b64 vcc, exec, s[2:3]
	v_mfma_f32_32x32x16_bf16 v[2:17], v[154:157], v[118:121], v[2:17]
	v_exp_f32_e32 v92, v92
	v_exp_f32_e32 v93, v93
	v_mfma_f32_32x32x16_bf16 v[2:17], v[150:153], v[122:125], v[2:17]
	v_exp_f32_e32 v94, v94
	v_exp_f32_e32 v95, v95
	v_mfma_f32_32x32x16_bf16 v[2:17], v[146:149], v[126:129], v[2:17]
	v_exp_f32_e32 v96, v96
	v_exp_f32_e32 v97, v97
	s_cbranch_vccnz .LBB0_979
	s_waitcnt lgkmcnt(0)
	ds_read_b128 v[114:117], v229 offset:96
	ds_read_b128 v[118:121], v229 offset:64
	ds_read_b128 v[122:125], v229 offset:32
	ds_read_b128 v[126:129], v229
	s_waitcnt lgkmcnt(3)
	v_pk_mul_f32 v[62:63], v[62:63], v[114:115]
	s_waitcnt lgkmcnt(2)
	v_pk_mul_f32 v[58:59], v[58:59], v[118:119]
	s_waitcnt lgkmcnt(1)
	v_pk_mul_f32 v[54:55], v[54:55], v[122:123]
	v_pk_mul_f32 v[64:65], v[64:65], v[116:117]
	v_pk_mul_f32 v[60:61], v[60:61], v[120:121]
	v_pk_mul_f32 v[56:57], v[56:57], v[124:125]
	s_waitcnt lgkmcnt(0)
	v_pk_mul_f32 v[52:53], v[52:53], v[128:129]
	v_pk_mul_f32 v[50:51], v[50:51], v[126:127]
	v_pk_mul_f32 v[46:47], v[46:47], v[114:115]
	v_pk_mul_f32 v[42:43], v[42:43], v[118:119]
	v_pk_mul_f32 v[38:39], v[38:39], v[122:123]
	v_pk_mul_f32 v[48:49], v[48:49], v[116:117]
	v_pk_mul_f32 v[44:45], v[44:45], v[120:121]
	v_pk_mul_f32 v[40:41], v[40:41], v[124:125]
	v_pk_mul_f32 v[36:37], v[36:37], v[128:129]
	v_pk_mul_f32 v[34:35], v[34:35], v[126:127]
	v_pk_mul_f32 v[30:31], v[30:31], v[114:115]
	v_pk_mul_f32 v[26:27], v[26:27], v[118:119]
	v_pk_mul_f32 v[22:23], v[22:23], v[122:123]
	v_pk_mul_f32 v[32:33], v[32:33], v[116:117]
	v_pk_mul_f32 v[28:29], v[28:29], v[120:121]
	v_pk_mul_f32 v[24:25], v[24:25], v[124:125]
	v_pk_mul_f32 v[20:21], v[20:21], v[128:129]
	v_pk_mul_f32 v[18:19], v[18:19], v[126:127]
	v_pk_mul_f32 v[14:15], v[14:15], v[114:115]
	v_pk_mul_f32 v[10:11], v[10:11], v[118:119]
	v_pk_mul_f32 v[6:7], v[6:7], v[122:123]
	v_pk_mul_f32 v[16:17], v[16:17], v[116:117]
	v_pk_mul_f32 v[12:13], v[12:13], v[120:121]
	v_pk_mul_f32 v[8:9], v[8:9], v[124:125]
	v_pk_mul_f32 v[4:5], v[4:5], v[128:129]
	v_pk_mul_f32 v[2:3], v[2:3], v[126:127]

.LBB0_1079:
	s_lshl_b32 s40, s2, 1
	v_add_u32_e32 v216, s40, v242
	ds_read_b64_tr_b16 v[210:211], v216 offset:24576
	ds_read_b64_tr_b16 v[212:213], v216 offset:25088
	s_waitcnt lgkmcnt(9)
	v_mfma_f32_32x32x16_bf16 v[130:145], v[206:209], v[174:177], v[66:81]
	v_add_f32_e32 v114, v98, v99
	v_add_f32_e32 v114, v100, v114
	v_add_f32_e32 v114, v101, v114
	v_add_f32_e32 v114, v102, v114
	v_add_f32_e32 v114, v103, v114
	v_cvt_pk_bf16_f32 v166, v98, v99
	v_cvt_pk_bf16_f32 v167, v100, v101
	ds_read_b64_tr_b16 v[206:207], v216 offset:28672
	ds_read_b64_tr_b16 v[208:209], v216 offset:29184
	v_add_f32_e32 v98, v104, v114
	s_waitcnt lgkmcnt(10)
	v_mfma_f32_32x32x16_bf16 v[114:129], v[198:201], v[174:177], v[66:81]
	v_add_f32_e32 v98, v105, v98
	v_add_f32_e32 v98, v106, v98
	v_add_f32_e32 v154, v107, v98
	v_cvt_pk_bf16_f32 v168, v102, v103
	v_cvt_pk_bf16_f32 v169, v104, v105
	ds_read_b64_tr_b16 v[98:99], v216 offset:25600
	ds_read_b64_tr_b16 v[100:101], v216 offset:26112
	s_waitcnt lgkmcnt(11)
	v_mfma_f32_32x32x16_bf16 v[130:145], v[202:205], v[170:173], v[130:145]
	v_add_f32_e32 v102, v108, v154
	v_add_f32_e32 v102, v109, v102
	v_add_f32_e32 v102, v110, v102
	v_add_f32_e32 v154, v111, v102
	v_cvt_pk_bf16_f32 v162, v106, v107
	v_cvt_pk_bf16_f32 v163, v108, v109
	ds_read_b64_tr_b16 v[102:103], v216 offset:29696
	ds_read_b64_tr_b16 v[104:105], v216 offset:30208
	s_waitcnt lgkmcnt(12)
	v_mfma_f32_32x32x16_bf16 v[114:129], v[194:197], v[170:173], v[114:129]
	v_add_f32_e32 v106, v112, v154
	v_add_f32_e32 v106, v113, v106
	v_add_f32_e32 v106, v82, v106
	v_add_f32_e32 v154, v83, v106
	v_cvt_pk_bf16_f32 v164, v110, v111
	v_cvt_pk_bf16_f32 v165, v112, v113
	ds_read_b64_tr_b16 v[106:107], v216 offset:26624
	ds_read_b64_tr_b16 v[108:109], v216 offset:27136
	s_waitcnt lgkmcnt(13)
	v_mfma_f32_32x32x16_bf16 v[130:145], v[190:193], v[150:153], v[130:145]
	v_add_f32_e32 v110, v84, v154
	v_add_f32_e32 v110, v85, v110
	v_add_f32_e32 v110, v86, v110
	v_add_f32_e32 v154, v87, v110
	v_cvt_pk_bf16_f32 v158, v82, v83
	v_cvt_pk_bf16_f32 v159, v84, v85
	ds_read_b64_tr_b16 v[110:111], v216 offset:30720
	ds_read_b64_tr_b16 v[112:113], v216 offset:31232
	s_waitcnt lgkmcnt(14)
	v_mfma_f32_32x32x16_bf16 v[114:129], v[186:189], v[150:153], v[114:129]
	v_add_f32_e32 v82, v88, v154
	v_add_f32_e32 v82, v89, v82
	v_add_f32_e32 v82, v90, v82
	v_add_f32_e32 v82, v91, v82
	v_cvt_pk_bf16_f32 v160, v86, v87
	v_cvt_pk_bf16_f32 v161, v88, v89
	ds_read_b64_tr_b16 v[86:87], v216 offset:27648
	ds_read_b64_tr_b16 v[88:89], v216 offset:28160
	s_waitcnt lgkmcnt(14)
	v_mfma_f32_32x32x16_bf16 v[130:145], v[182:185], v[146:149], v[130:145]
	v_add_f32_e32 v82, v92, v82
	v_add_f32_e32 v82, v93, v82
	v_add_f32_e32 v82, v94, v82
	v_add_f32_e32 v82, v95, v82
	v_cvt_pk_bf16_f32 v154, v90, v91
	v_cvt_pk_bf16_f32 v155, v92, v93
	ds_read_b64_tr_b16 v[90:91], v216 offset:31744
	ds_read_b64_tr_b16 v[92:93], v216 offset:32256
	v_mfma_f32_32x32x16_bf16 v[114:129], v[178:181], v[146:149], v[114:129]
	v_add_f32_e32 v82, v96, v82
	v_add_f32_e32 v82, v97, v82
	v_add_f32_e32 v84, 0, v82
	v_cvt_pk_bf16_f32 v156, v94, v95
	v_cvt_pk_bf16_f32 v157, v96, v97
	v_lshl_add_u64 v[218:219], v[226:227], 0, s[34:35]
	v_lshl_add_u64 v[82:83], v[218:219], 0, s[22:23]
	s_add_i32 s2, s48, s44
	v_lshl_add_u64 v[216:217], v[214:215], 0, s[34:35]
	s_mov_b32 s3, m0
	s_mov_b32 m0, s2
	s_nop 0
	global_load_lds_dwordx4 v[82:83], off
	s_mov_b32 m0, s3
	v_lshl_add_u64 v[82:83], v[216:217], 0, s[24:25]
	s_lshl_b32 s2, s43, 1
	s_add_i32 s2, s2, s45
	s_mov_b32 s3, m0
	s_mov_b32 m0, s2
	s_nop 0
	global_load_lds_dwordx4 v[82:83], off
	s_mov_b32 m0, s3
	v_lshl_add_u64 v[82:83], v[216:217], 0, s[26:27]
	s_addk_i32 s2, 0x2000
	s_mov_b32 s3, m0
	s_mov_b32 m0, s2
	s_nop 0
	global_load_lds_dwordx4 v[82:83], off
	s_mov_b32 m0, s3
	s_waitcnt lgkmcnt(14)
	v_mfma_f32_32x32x16_bf16 v[50:65], v[166:169], v[210:213], v[50:65]
	v_max_f32_e32 v82, v131, v131
	v_max_f32_e32 v83, v130, v130
	v_max_f32_e32 v82, v83, v82
	v_max3_f32 v83, v132, v133, v115
	v_max3_f32 v82, v82, v114, v116
	v_max3_f32 v82, v82, v117, v134
	v_max3_f32 v83, v83, v136, v137
	v_max3_f32 v82, v82, v135, v118
	v_max3_f32 v83, v83, v120, v121
	v_max3_f32 v82, v82, v119, v138
	s_waitcnt lgkmcnt(12)
	v_mfma_f32_32x32x16_bf16 v[34:49], v[166:169], v[206:209], v[34:49]
	v_max3_f32 v83, v83, v140, v141
	v_max3_f32 v82, v82, v139, v122
	v_max3_f32 v83, v83, v124, v125
	v_max3_f32 v82, v82, v123, v142
	v_max3_f32 v83, v83, v144, v145
	v_max3_f32 v82, v82, v143, v126
	v_max3_f32 v83, v83, v128, v129
	v_max3_f32 v82, v82, v127, v83
	v_mov_b32_e32 v83, v82
	s_nop 1
	v_permlane32_swap_b32_e32 v82, v83
	v_max_f32_e32 v83, v83, v83
	v_max_f32_e32 v82, v82, v82
	v_max_f32_e32 v82, v82, v83
	v_cmp_lt_f32_e32 vcc, s15, v82
	s_cmp_lg_u64 vcc, 0
	v_add_f32_e32 v230, v244, v84
	s_cselect_b64 s[2:3], -1, 0
	s_cbranch_vccnz .LBB0_1087
.LBB0_1080:
	v_add_u32_e32 v94, s43, v241
	ds_read_b128 v[82:85], v94
	ds_read_b128 v[198:201], v94 offset:512
	s_waitcnt lgkmcnt(12)
	v_mfma_f32_32x32x16_bf16 v[50:65], v[162:165], v[98:101], v[50:65]
	v_exp_f32_e32 v130, v130
	v_exp_f32_e32 v131, v131
	v_exp_f32_e32 v132, v132
	ds_read_b128 v[202:205], v94 offset:2048
	ds_read_b128 v[194:197], v94 offset:2560
	s_waitcnt lgkmcnt(12)
	v_mfma_f32_32x32x16_bf16 v[34:49], v[162:165], v[102:105], v[34:49]
	v_exp_f32_e32 v133, v133
	v_exp_f32_e32 v134, v134
	v_exp_f32_e32 v135, v135
	ds_read_b128 v[190:193], v94 offset:4096
	ds_read_b128 v[186:189], v94 offset:4608
	s_waitcnt lgkmcnt(12)
	v_mfma_f32_32x32x16_bf16 v[50:65], v[158:161], v[106:109], v[50:65]
	v_exp_f32_e32 v136, v136
	v_exp_f32_e32 v137, v137
	v_exp_f32_e32 v138, v138
	ds_read_b128 v[182:185], v94 offset:6144
	ds_read_b128 v[178:181], v94 offset:6656
	s_waitcnt lgkmcnt(12)
	v_mfma_f32_32x32x16_bf16 v[34:49], v[158:161], v[110:113], v[34:49]
	v_exp_f32_e32 v139, v139
	v_exp_f32_e32 v140, v140
	v_exp_f32_e32 v141, v141
	s_waitcnt lgkmcnt(10)
	v_mfma_f32_32x32x16_bf16 v[50:65], v[154:157], v[86:89], v[50:65]
	v_exp_f32_e32 v142, v142
	v_exp_f32_e32 v143, v143
	s_waitcnt lgkmcnt(8)
	v_mfma_f32_32x32x16_bf16 v[34:49], v[154:157], v[90:93], v[34:49]
	v_exp_f32_e32 v144, v144
	v_exp_f32_e32 v145, v145
	v_add_u32_e32 v102, s40, v228
	ds_read_b64_tr_b16 v[86:87],v102 offset:0
	ds_read_b64_tr_b16 v[88:89],v102 offset:512
	ds_read_b64_tr_b16 v[90:91],v102 offset:1024
	ds_read_b64_tr_b16 v[92:93],v102 offset:1536
	ds_read_b64_tr_b16 v[94:95],v102 offset:2048
	ds_read_b64_tr_b16 v[96:97],v102 offset:2560
	ds_read_b64_tr_b16 v[98:99],v102 offset:3072
	ds_read_b64_tr_b16 v[100:101],v102 offset:3584
	s_waitcnt lgkmcnt(0)
	s_nop 0
	v_mfma_f32_32x32x16_bf16 v[18:33], v[166:169], v[86:89], v[18:33]
	v_exp_f32_e32 v114, v114
	v_exp_f32_e32 v115, v115
	ds_read_b64_tr_b16 v[86:87],v102 offset:4096
	ds_read_b64_tr_b16 v[88:89],v102 offset:4608
	v_mfma_f32_32x32x16_bf16 v[18:33], v[162:165], v[90:93], v[18:33]
	v_exp_f32_e32 v116, v116
	v_exp_f32_e32 v117, v117
	ds_read_b64_tr_b16 v[90:91],v102 offset:5120
	ds_read_b64_tr_b16 v[92:93],v102 offset:5632
	v_mfma_f32_32x32x16_bf16 v[18:33], v[158:161], v[94:97], v[18:33]
	v_exp_f32_e32 v118, v118
	v_exp_f32_e32 v119, v119
	ds_read_b64_tr_b16 v[94:95],v102 offset:6144
	ds_read_b64_tr_b16 v[96:97],v102 offset:6656
	v_mfma_f32_32x32x16_bf16 v[18:33], v[154:157], v[98:101], v[18:33]
	v_exp_f32_e32 v120, v120
	v_exp_f32_e32 v121, v121
	ds_read_b64_tr_b16 v[98:99],v102 offset:7168
	ds_read_b64_tr_b16 v[100:101],v102 offset:7680
	s_waitcnt lgkmcnt(0)
	v_mfma_f32_32x32x16_bf16 v[2:17], v[166:169], v[86:89], v[2:17]
	v_exp_f32_e32 v122, v122
	v_exp_f32_e32 v123, v123
	s_waitcnt vmcnt(3) lgkmcnt(0)
	s_barrier
	s_andn2_b64 vcc, exec, s[2:3]
	v_add_u32_e32 v229, s39, v243
	v_mfma_f32_32x32x16_bf16 v[2:17], v[162:165], v[90:93], v[2:17]
	v_exp_f32_e32 v124, v124
	v_exp_f32_e32 v125, v125
	v_mfma_f32_32x32x16_bf16 v[2:17], v[158:161], v[94:97], v[2:17]
	v_exp_f32_e32 v126, v126
	v_exp_f32_e32 v127, v127
	v_mfma_f32_32x32x16_bf16 v[2:17], v[154:157], v[98:101], v[2:17]
	v_exp_f32_e32 v128, v128
	v_exp_f32_e32 v129, v129
	s_cbranch_vccnz .LBB0_1082
	s_waitcnt lgkmcnt(0)
	ds_read_b128 v[86:89], v229 offset:96
	ds_read_b128 v[90:93], v229 offset:64
	ds_read_b128 v[94:97], v229 offset:32
	ds_read_b128 v[98:101], v229
	s_waitcnt lgkmcnt(3)
	v_pk_mul_f32 v[62:63], v[62:63], v[86:87]
	s_waitcnt lgkmcnt(2)
	v_pk_mul_f32 v[58:59], v[58:59], v[90:91]
	s_waitcnt lgkmcnt(1)
	v_pk_mul_f32 v[54:55], v[54:55], v[94:95]
	v_pk_mul_f32 v[64:65], v[64:65], v[88:89]
	v_pk_mul_f32 v[60:61], v[60:61], v[92:93]
	v_pk_mul_f32 v[56:57], v[56:57], v[96:97]
	s_waitcnt lgkmcnt(0)
	v_pk_mul_f32 v[52:53], v[52:53], v[100:101]
	v_pk_mul_f32 v[50:51], v[50:51], v[98:99]
	v_pk_mul_f32 v[46:47], v[46:47], v[86:87]
	v_pk_mul_f32 v[42:43], v[42:43], v[90:91]
	v_pk_mul_f32 v[38:39], v[38:39], v[94:95]
	v_pk_mul_f32 v[48:49], v[48:49], v[88:89]
	v_pk_mul_f32 v[44:45], v[44:45], v[92:93]
	v_pk_mul_f32 v[40:41], v[40:41], v[96:97]
	v_pk_mul_f32 v[36:37], v[36:37], v[100:101]
	v_pk_mul_f32 v[34:35], v[34:35], v[98:99]
	v_pk_mul_f32 v[30:31], v[30:31], v[86:87]
	v_pk_mul_f32 v[26:27], v[26:27], v[90:91]
	v_pk_mul_f32 v[22:23], v[22:23], v[94:95]
	v_pk_mul_f32 v[32:33], v[32:33], v[88:89]
	v_pk_mul_f32 v[28:29], v[28:29], v[92:93]
	v_pk_mul_f32 v[24:25], v[24:25], v[96:97]
	v_pk_mul_f32 v[20:21], v[20:21], v[100:101]
	v_pk_mul_f32 v[18:19], v[18:19], v[98:99]
	v_pk_mul_f32 v[14:15], v[14:15], v[86:87]
	v_pk_mul_f32 v[10:11], v[10:11], v[90:91]
	v_pk_mul_f32 v[6:7], v[6:7], v[94:95]
	v_pk_mul_f32 v[16:17], v[16:17], v[88:89]
	v_pk_mul_f32 v[12:13], v[12:13], v[92:93]
	v_pk_mul_f32 v[8:9], v[8:9], v[96:97]
	v_pk_mul_f32 v[4:5], v[4:5], v[100:101]
	v_pk_mul_f32 v[2:3], v[2:3], v[98:99]
.LBB0_1082:
	s_add_i32 s2, s43, 0x2000
	s_cmpk_lg_i32 s43, 0x4000
	s_cselect_b32 s40, s2, 0
	s_lshl_b32 s47, s48, 1
	v_add_u32_e32 v231, s47, v242
	ds_read_b64_tr_b16 v[210:211], v231 offset:24576
	ds_read_b64_tr_b16 v[212:213], v231 offset:25088
	s_waitcnt lgkmcnt(9)
	v_mfma_f32_32x32x16_bf16 v[98:113], v[82:85], v[174:177], v[66:81]
	v_add_f32_e32 v86, v130, v131
	v_add_f32_e32 v86, v132, v86
	v_add_f32_e32 v86, v133, v86
	v_add_f32_e32 v86, v134, v86
	v_add_f32_e32 v86, v135, v86
	v_cvt_pk_bf16_f32 v166, v130, v131
	v_cvt_pk_bf16_f32 v167, v132, v133
	ds_read_b64_tr_b16 v[206:207], v231 offset:28672
	ds_read_b64_tr_b16 v[208:209], v231 offset:29184
	v_add_f32_e32 v82, v136, v86
	v_add_f32_e32 v82, v137, v82
	v_add_f32_e32 v82, v138, v82
	v_add_f32_e32 v154, v139, v82
	s_waitcnt lgkmcnt(10)
	v_mfma_f32_32x32x16_bf16 v[82:97], v[198:201], v[174:177], v[66:81]
	v_cvt_pk_bf16_f32 v168, v134, v135
	v_cvt_pk_bf16_f32 v169, v136, v137
	ds_read_b64_tr_b16 v[130:131], v231 offset:25600
	ds_read_b64_tr_b16 v[132:133], v231 offset:26112
	s_waitcnt lgkmcnt(11)
	v_mfma_f32_32x32x16_bf16 v[98:113], v[202:205], v[170:173], v[98:113]
	v_add_f32_e32 v134, v140, v154
	v_add_f32_e32 v134, v141, v134
	v_add_f32_e32 v134, v142, v134
	v_add_f32_e32 v154, v143, v134
	v_cvt_pk_bf16_f32 v162, v138, v139
	v_cvt_pk_bf16_f32 v163, v140, v141
	ds_read_b64_tr_b16 v[134:135], v231 offset:29696
	ds_read_b64_tr_b16 v[136:137], v231 offset:30208
	s_waitcnt lgkmcnt(12)
	v_mfma_f32_32x32x16_bf16 v[82:97], v[194:197], v[170:173], v[82:97]
	v_add_f32_e32 v138, v144, v154
	v_add_f32_e32 v138, v145, v138
	v_add_f32_e32 v138, v114, v138
	v_add_f32_e32 v154, v115, v138
	v_cvt_pk_bf16_f32 v164, v142, v143
	v_cvt_pk_bf16_f32 v165, v144, v145
	ds_read_b64_tr_b16 v[138:139], v231 offset:26624
	ds_read_b64_tr_b16 v[140:141], v231 offset:27136
	s_waitcnt lgkmcnt(13)
	v_mfma_f32_32x32x16_bf16 v[98:113], v[190:193], v[150:153], v[98:113]
	v_add_f32_e32 v142, v116, v154
	v_add_f32_e32 v142, v117, v142
	v_add_f32_e32 v142, v118, v142
	v_add_f32_e32 v142, v119, v142
	v_cvt_pk_bf16_f32 v158, v114, v115
	v_cvt_pk_bf16_f32 v159, v116, v117
	ds_read_b64_tr_b16 v[114:115], v231 offset:30720
	ds_read_b64_tr_b16 v[116:117], v231 offset:31232
	s_waitcnt lgkmcnt(14)
	v_mfma_f32_32x32x16_bf16 v[82:97], v[186:189], v[150:153], v[82:97]
	v_add_f32_e32 v142, v120, v142
	v_add_f32_e32 v142, v121, v142
	v_add_f32_e32 v142, v122, v142
	v_add_f32_e32 v142, v123, v142
	v_cvt_pk_bf16_f32 v160, v118, v119
	v_cvt_pk_bf16_f32 v161, v120, v121
	ds_read_b64_tr_b16 v[118:119], v231 offset:27648
	ds_read_b64_tr_b16 v[120:121], v231 offset:28160
	s_waitcnt lgkmcnt(14)
	v_mfma_f32_32x32x16_bf16 v[98:113], v[182:185], v[146:149], v[98:113]
	v_add_f32_e32 v142, v124, v142
	v_add_f32_e32 v142, v125, v142
	v_add_f32_e32 v142, v126, v142
	v_add_f32_e32 v142, v127, v142
	v_cvt_pk_bf16_f32 v154, v122, v123
	v_cvt_pk_bf16_f32 v155, v124, v125
	ds_read_b64_tr_b16 v[122:123], v231 offset:31744
	ds_read_b64_tr_b16 v[124:125], v231 offset:32256
	v_mfma_f32_32x32x16_bf16 v[82:97], v[178:181], v[146:149], v[82:97]
	v_add_f32_e32 v142, v128, v142
	v_add_f32_e32 v142, v129, v142
	v_add_f32_e32 v142, 0, v142
	v_cvt_pk_bf16_f32 v156, v126, v127
	v_cvt_pk_bf16_f32 v157, v128, v129
	s_mov_b64 s[2:3], 0x50000
	v_lshl_add_u64 v[126:127], v[218:219], 0, s[2:3]
	s_add_i32 s2, s43, s44
	s_mov_b32 s3, m0
	s_mov_b32 m0, s2
	s_nop 0
	global_load_lds_dwordx4 v[126:127], off
	s_mov_b32 m0, s3
	s_mov_b64 s[2:3], 0x5830000
	v_lshl_add_u64 v[126:127], v[216:217], 0, s[2:3]
	s_lshl_b32 s2, s40, 1
	s_add_i32 s36, s2, s45
	s_mov_b32 s2, m0
	s_mov_b32 m0, s36
	s_nop 0
	global_load_lds_dwordx4 v[126:127], off
	s_mov_b32 m0, s2
	s_mov_b64 s[2:3], 0x5830080
	v_lshl_add_u64 v[126:127], v[216:217], 0, s[2:3]
	s_add_i32 s2, s36, 0x2000
	s_mov_b32 s3, m0
	s_mov_b32 m0, s2
	s_nop 0
	global_load_lds_dwordx4 v[126:127], off
	s_mov_b32 m0, s3
	s_waitcnt lgkmcnt(14)
	v_mfma_f32_32x32x16_bf16 v[50:65], v[166:169], v[210:213], v[50:65]
	v_max_f32_e32 v126, v99, v99
	v_max_f32_e32 v127, v98, v98
	v_max_f32_e32 v126, v127, v126
	v_max3_f32 v127, v100, v101, v83
	v_max3_f32 v126, v126, v82, v84
	v_max3_f32 v126, v126, v85, v102
	v_max3_f32 v127, v127, v104, v105
	v_max3_f32 v126, v126, v103, v86
	v_max3_f32 v127, v127, v88, v89
	v_max3_f32 v126, v126, v87, v106
	s_waitcnt lgkmcnt(12)
	v_mfma_f32_32x32x16_bf16 v[34:49], v[166:169], v[206:209], v[34:49]
	v_max3_f32 v127, v127, v108, v109
	v_max3_f32 v126, v126, v107, v90
	v_max3_f32 v127, v127, v92, v93
	v_max3_f32 v126, v126, v91, v110
	v_max3_f32 v127, v127, v112, v113
	v_max3_f32 v126, v126, v111, v94
	v_max3_f32 v127, v127, v96, v97
	v_max3_f32 v126, v126, v95, v127
	v_mov_b32_e32 v127, v126
	s_nop 1
	v_permlane32_swap_b32_e32 v126, v127
	v_max_f32_e32 v127, v127, v127
	v_max_f32_e32 v126, v126, v126
	v_max_f32_e32 v126, v126, v127
	v_cmp_lt_f32_e32 vcc, s15, v126
	s_cmp_lg_u64 vcc, 0
	v_add_f32_e32 v244, v230, v142
	s_cselect_b64 s[2:3], -1, 0
	s_cbranch_vccnz .LBB0_1090
.LBB0_1083:
	v_add_u32_e32 v126, s40, v241
	ds_read_b128 v[206:209], v126
	ds_read_b128 v[198:201], v126 offset:512
	s_waitcnt lgkmcnt(12)
	v_mfma_f32_32x32x16_bf16 v[50:65], v[162:165], v[130:133], v[50:65]
	v_exp_f32_e32 v98, v98
	v_exp_f32_e32 v99, v99
	v_exp_f32_e32 v100, v100
	ds_read_b128 v[202:205], v126 offset:2048
	ds_read_b128 v[194:197], v126 offset:2560
	s_waitcnt lgkmcnt(12)
	v_mfma_f32_32x32x16_bf16 v[34:49], v[162:165], v[134:137], v[34:49]
	v_exp_f32_e32 v101, v101
	v_exp_f32_e32 v102, v102
	v_exp_f32_e32 v103, v103
	ds_read_b128 v[190:193], v126 offset:4096
	ds_read_b128 v[186:189], v126 offset:4608
	s_waitcnt lgkmcnt(12)
	v_mfma_f32_32x32x16_bf16 v[50:65], v[158:161], v[138:141], v[50:65]
	v_exp_f32_e32 v104, v104
	v_exp_f32_e32 v105, v105
	v_exp_f32_e32 v106, v106
	ds_read_b128 v[182:185], v126 offset:6144
	ds_read_b128 v[178:181], v126 offset:6656
	s_waitcnt lgkmcnt(12)
	v_mfma_f32_32x32x16_bf16 v[34:49], v[158:161], v[114:117], v[34:49]
	v_exp_f32_e32 v107, v107
	v_exp_f32_e32 v108, v108
	v_exp_f32_e32 v109, v109
	s_waitcnt lgkmcnt(10)
	v_mfma_f32_32x32x16_bf16 v[50:65], v[154:157], v[118:121], v[50:65]
	v_exp_f32_e32 v110, v110
	v_exp_f32_e32 v111, v111
	s_waitcnt lgkmcnt(8)
	v_mfma_f32_32x32x16_bf16 v[34:49], v[154:157], v[122:125], v[34:49]
	v_exp_f32_e32 v112, v112
	v_exp_f32_e32 v113, v113
	v_add_u32_e32 v130, s47, v228
	ds_read_b64_tr_b16 v[114:115],v130 offset:0
	ds_read_b64_tr_b16 v[116:117],v130 offset:512
	ds_read_b64_tr_b16 v[118:119],v130 offset:1024
	ds_read_b64_tr_b16 v[120:121],v130 offset:1536
	ds_read_b64_tr_b16 v[122:123],v130 offset:2048
	ds_read_b64_tr_b16 v[124:125],v130 offset:2560
	ds_read_b64_tr_b16 v[126:127],v130 offset:3072
	ds_read_b64_tr_b16 v[128:129],v130 offset:3584
	s_waitcnt lgkmcnt(0)
	s_nop 0
	v_mfma_f32_32x32x16_bf16 v[18:33], v[166:169], v[114:117], v[18:33]
	v_exp_f32_e32 v82, v82
	v_exp_f32_e32 v83, v83
	ds_read_b64_tr_b16 v[114:115],v130 offset:4096
	ds_read_b64_tr_b16 v[116:117],v130 offset:4608
	v_mfma_f32_32x32x16_bf16 v[18:33], v[162:165], v[118:121], v[18:33]
	v_exp_f32_e32 v84, v84
	v_exp_f32_e32 v85, v85
	ds_read_b64_tr_b16 v[118:119],v130 offset:5120
	ds_read_b64_tr_b16 v[120:121],v130 offset:5632
	v_mfma_f32_32x32x16_bf16 v[18:33], v[158:161], v[122:125], v[18:33]
	v_exp_f32_e32 v86, v86
	v_exp_f32_e32 v87, v87
	ds_read_b64_tr_b16 v[122:123],v130 offset:6144
	ds_read_b64_tr_b16 v[124:125],v130 offset:6656
	v_mfma_f32_32x32x16_bf16 v[18:33], v[154:157], v[126:129], v[18:33]
	v_exp_f32_e32 v88, v88
	v_exp_f32_e32 v89, v89
	ds_read_b64_tr_b16 v[126:127],v130 offset:7168
	ds_read_b64_tr_b16 v[128:129],v130 offset:7680
	s_waitcnt lgkmcnt(0)
	v_mfma_f32_32x32x16_bf16 v[2:17], v[166:169], v[114:117], v[2:17]
	v_exp_f32_e32 v90, v90
	v_exp_f32_e32 v91, v91
	s_waitcnt vmcnt(3) lgkmcnt(0)
	s_barrier
	s_andn2_b64 vcc, exec, s[2:3]
	v_mfma_f32_32x32x16_bf16 v[2:17], v[162:165], v[118:121], v[2:17]
	v_exp_f32_e32 v92, v92
	v_exp_f32_e32 v93, v93
	v_mfma_f32_32x32x16_bf16 v[2:17], v[158:161], v[122:125], v[2:17]
	v_exp_f32_e32 v94, v94
	v_exp_f32_e32 v95, v95
	v_mfma_f32_32x32x16_bf16 v[2:17], v[154:157], v[126:129], v[2:17]
	v_exp_f32_e32 v96, v96
	v_exp_f32_e32 v97, v97
	s_cbranch_vccnz .LBB0_1085
	s_waitcnt lgkmcnt(0)
	ds_read_b128 v[114:117], v229 offset:96
	ds_read_b128 v[118:121], v229 offset:64
	ds_read_b128 v[122:125], v229 offset:32
	ds_read_b128 v[126:129], v229
	s_waitcnt lgkmcnt(3)
	v_pk_mul_f32 v[62:63], v[62:63], v[114:115]
	s_waitcnt lgkmcnt(2)
	v_pk_mul_f32 v[58:59], v[58:59], v[118:119]
	s_waitcnt lgkmcnt(1)
	v_pk_mul_f32 v[54:55], v[54:55], v[122:123]
	v_pk_mul_f32 v[64:65], v[64:65], v[116:117]
	v_pk_mul_f32 v[60:61], v[60:61], v[120:121]
	v_pk_mul_f32 v[56:57], v[56:57], v[124:125]
	s_waitcnt lgkmcnt(0)
	v_pk_mul_f32 v[52:53], v[52:53], v[128:129]
	v_pk_mul_f32 v[50:51], v[50:51], v[126:127]
	v_pk_mul_f32 v[46:47], v[46:47], v[114:115]
	v_pk_mul_f32 v[42:43], v[42:43], v[118:119]
	v_pk_mul_f32 v[38:39], v[38:39], v[122:123]
	v_pk_mul_f32 v[48:49], v[48:49], v[116:117]
	v_pk_mul_f32 v[44:45], v[44:45], v[120:121]
	v_pk_mul_f32 v[40:41], v[40:41], v[124:125]
	v_pk_mul_f32 v[36:37], v[36:37], v[128:129]
	v_pk_mul_f32 v[34:35], v[34:35], v[126:127]
	v_pk_mul_f32 v[30:31], v[30:31], v[114:115]
	v_pk_mul_f32 v[26:27], v[26:27], v[118:119]
	v_pk_mul_f32 v[22:23], v[22:23], v[122:123]
	v_pk_mul_f32 v[32:33], v[32:33], v[116:117]
	v_pk_mul_f32 v[28:29], v[28:29], v[120:121]
	v_pk_mul_f32 v[24:25], v[24:25], v[124:125]
	v_pk_mul_f32 v[20:21], v[20:21], v[128:129]
	v_pk_mul_f32 v[18:19], v[18:19], v[126:127]
	v_pk_mul_f32 v[14:15], v[14:15], v[114:115]
	v_pk_mul_f32 v[10:11], v[10:11], v[118:119]
	v_pk_mul_f32 v[6:7], v[6:7], v[122:123]
	v_pk_mul_f32 v[16:17], v[16:17], v[116:117]
	v_pk_mul_f32 v[12:13], v[12:13], v[120:121]
	v_pk_mul_f32 v[8:9], v[8:9], v[124:125]
	v_pk_mul_f32 v[4:5], v[4:5], v[128:129]
	v_pk_mul_f32 v[2:3], v[2:3], v[126:127]
